# weight-prep split v2: phase 0 of layers 1-3 only converts items <4096; workgroups 128-255 do the remaining transposes plus pool-weight, lru-gate-weight and decay-table prep in their idle slot after ph
# speedup vs baseline: 1.0026x; 1.0026x over previous
; __device__ __forceinline__ bf16_t f2bf(float f) { return (bf16_t)(pk2(f, 0.f) & 0xffffu); }
; __device__ __forceinline__ void wprep_phase(const WArgs& a, LAS float* scr, int gw, int NGW, int lane, int gtid, int NGT) {
;     ...
;     for (int e = gtid; e < 256; e += NGT) a.cdec[e] = -8.0f * log1pf(expf(-a.lam[e]));
;     for (int e = gtid; e < 1024 * 256; e += NGT) { const int n = e & 1023, k = e >> 10, gI = k >> 6, cI = k & 63;
;         const float* wg = a.w_pgrp + (gI * 64 + cI) * 64; float s = 0.f;
; #pragma unroll 16
;         for (int d = 0; d < 64; ++d) s += wg[d] * a.pscale[gI * 64 + d] * a.w_pproj[(size_t)(gI * 64 + d) * 1024 + n];
;         a.W[WO_CAT + (size_t)n * 1024 + k] = f2bf(s); }
;     for (int e = gtid; e < 512 * 256; e += NGT) { const int k = e & 255, np = e >> 8, pn = np >> 8, x = np & 255, chn = pn * 128 + (x & 127);
;         float v = 0.f; if ((k >> 6) == (chn >> 6)) { const float* w = (x < 128) ? a.w_a : a.w_x; v = w[((chn >> 6) * 64 + (k & 63)) * 64 + (chn & 63)]; }
;         a.W[WO_AX + (size_t)np * 256 + k] = f2bf(v); }
.Lwp_x:
	v_readlane_b32 s94, v255, 0
	s_waitcnt vmcnt(0) lgkmcnt(0)
	v_lshl_add_u32 v2, s2, 9, v81
	s_movk_i32 s0, 0x100
	s_lshl_b32 s36, s35, 9
	v_readlane_b32 s1, v255, 12
	s_cmp_eq_u32 s1, 2
	s_cbranch_scc0 .Lwp_y
	v_add_u32_e32 v2, 0x100000, v2
.Lwp_y:
	s_cmp_eq_u32 s1, 1
	s_cbranch_scc0 .Lwp_z
	v_add_u32_e32 v2, 0xffff0000, v2
	s_lshr_b32 s36, s36, 1
.Lwp_z:
	v_cmp_gt_i32_e32 vcc, s0, v2
	s_and_saveexec_b64 s[20:21], vcc
	s_mov_b32 s48, 0x7f800000
	s_mov_b32 s52, 0x3f2aaaab
	s_mov_b32 s53, 0x3f317218
	s_cbranch_execz .LBB0_701
	v_readlane_b32 s4, v253, 32
	s_lshl_b64 s[0:1], s[30:31], 2
	v_readlane_b32 s6, v253, 34
	v_readlane_b32 s7, v253, 35
	s_add_u32 s30, s6, s0
	s_addc_u32 s31, s7, s1
	v_ashrrev_i32_e32 v3, 31, v2
	s_ashr_i32 s37, s36, 31
	v_lshlrev_b64 v[4:5], 2, v[2:3]
	s_lshl_b64 s[38:39], s[36:37], 2
	s_mov_b64 s[40:41], 0
	v_mov_b32_e32 v0, v2
	v_readlane_b32 s5, v253, 33
	v_readlane_b32 s8, v253, 36
	v_readlane_b32 s9, v253, 37
	v_readlane_b32 s10, v253, 38
	v_readlane_b32 s11, v253, 39
	v_readlane_b32 s12, v253, 40
	v_readlane_b32 s13, v253, 41
	v_readlane_b32 s14, v253, 42
	v_readlane_b32 s15, v253, 43
	v_readlane_b32 s16, v253, 44
	v_readlane_b32 s17, v253, 45
	v_readlane_b32 s18, v253, 46
	v_readlane_b32 s19, v253, 47
